# v17 plus: rescale fast path for the leading wave group's second tile, ballot s_cselect moved into the rare block (second-tile max chain left as the compiler wrote it)
# speedup vs baseline: 1.0056x; 1.0056x over previous
; #define QSTEP(d, A, B, NA, NB) do { if ((d) + 2 < 12) { NA = KLD((d) + 2, 0); NB = KLD((d) + 2, 1); } SBAR(); \
;     p0 = __builtin_amdgcn_mfma_f32_32x32x16_bf16(A, qr[d], p0, 0, 0, 0); p1 = __builtin_amdgcn_mfma_f32_32x32x16_bf16(B, qr[d], p1, 0, 0, 0); SBAR(); } while (0)
; __device__ __forceinline__ void partialSM(f32x16& p0, f32x16& p1, float& m_reg, float& mn, float& alpha) {
;   constexpr float C = SCALE * 1.4426950408889634f;
;   float pmax = p0[0];
; #pragma unroll
;   for (int r = 1; r < 16; ++r) pmax = fmaxf(pmax, p0[r]);
; #pragma unroll
;   for (int r = 0; r < 16; ++r) pmax = fmaxf(pmax, p1[r]);
;   { auto rr = __builtin_amdgcn_permlane32_swap(__float_as_uint(pmax), __float_as_uint(pmax), false, false);
;     pmax = fmaxf(__uint_as_float(rr[0]), __uint_as_float(rr[1])); }
;   if (__builtin_expect(__all(pmax - m_reg <= THR / SCALE), 1)) { mn = m_reg; alpha = 1.f; }
;   else { mn = fmaxf(m_reg, pmax); alpha = __builtin_amdgcn_exp2f((m_reg - mn) * C); m_reg = mn; }
; __device__ __forceinline__ void qkt2(f32x16& p0, f32x16& p1, const char* Ks, const bf16x8* qr, const int* kb4) {
;     ...
;   QSTEP(0, a0, b0, a2, b2); QSTEP(1, a1, b1, a0, b0); QSTEP(2, a2, b2, a1, b1);
;   QSTEP(3, a0, b0, a2, b2); QSTEP(4, a1, b1, a0, b0); QSTEP(5, a2, b2, a1, b1);
;   QSTEP(6, a0, b0, a2, b2); QSTEP(7, a1, b1, a0, b0); QSTEP(8, a2, b2, a1, b1);
;   QSTEP(9, a0, b0, a2, b2); QSTEP(10, a1, b1, a0, b0); QSTEP(11, a2, b2, a1, b1);
.LBB0_447:
	s_waitcnt lgkmcnt(5)
	v_mfma_f32_32x32x16_bf16 v[80:95], v[194:197], v[112:115], v[80:95]
	v_mfma_f32_32x32x16_bf16 v[64:79], v[224:227], v[112:115], v[64:79]
	ds_read_b128 v[194:197], v207 offset:57472
	ds_read_b128 v[224:227], v219 offset:12416
	s_waitcnt lgkmcnt(4)
	v_mfma_f32_32x32x16_bf16 v[80:95], v[228:231], v[116:119], v[80:95]
	v_mfma_f32_32x32x16_bf16 v[64:79], v[232:235], v[116:119], v[64:79]
	ds_read_b128 v[228:231], v210 offset:57600
	ds_read_b128 v[232:235], v216 offset:12544
	s_waitcnt lgkmcnt(4)
	v_mfma_f32_32x32x16_bf16 v[80:95], v[236:239], v[120:123], v[80:95]
	v_mfma_f32_32x32x16_bf16 v[64:79], v[240:243], v[120:123], v[64:79]
	ds_read_b128 v[236:239], v209 offset:57600
	ds_read_b128 v[240:243], v217 offset:12544
	s_waitcnt lgkmcnt(4)
	v_mfma_f32_32x32x16_bf16 v[80:95], v[194:197], v[124:127], v[80:95]
	v_mfma_f32_32x32x16_bf16 v[64:79], v[224:227], v[124:127], v[64:79]
	ds_read_b128 v[194:197], v208 offset:57600
	ds_read_b128 v[224:227], v218 offset:12544
	s_waitcnt lgkmcnt(4)
	v_mfma_f32_32x32x16_bf16 v[80:95], v[228:231], v[132:135], v[80:95]
	v_mfma_f32_32x32x16_bf16 v[64:79], v[232:235], v[132:135], v[64:79]
	ds_read_b128 v[228:231], v207 offset:57600
	ds_read_b128 v[232:235], v219 offset:12544
	s_waitcnt lgkmcnt(4)
	v_mfma_f32_32x32x16_bf16 v[80:95], v[236:239], v[140:143], v[80:95]
	v_mfma_f32_32x32x16_bf16 v[64:79], v[240:243], v[140:143], v[64:79]
	s_waitcnt lgkmcnt(2)
	v_mfma_f32_32x32x16_bf16 v[80:95], v[194:197], v[128:131], v[80:95]
	v_mfma_f32_32x32x16_bf16 v[64:79], v[224:227], v[128:131], v[64:79]
	s_waitcnt lgkmcnt(0)
	v_mfma_f32_32x32x16_bf16 v[80:95], v[228:231], v[136:139], v[80:95]
	v_mfma_f32_32x32x16_bf16 v[64:79], v[232:235], v[136:139], v[64:79]
	s_nop 9
	v_max_f32_e32 v194, v81, v81
	v_max_f32_e32 v195, v80, v80
	v_max_f32_e32 v194, v195, v194
	v_max3_f32 v194, v194, v82, v83
	v_max3_f32 v194, v194, v84, v85
	v_max3_f32 v194, v194, v86, v87
	v_max3_f32 v194, v194, v88, v89
	v_max3_f32 v194, v194, v90, v91
	v_max3_f32 v194, v194, v92, v93
	v_max3_f32 v194, v194, v94, v95
	v_max3_f32 v194, v194, v64, v65
	v_max3_f32 v194, v194, v66, v67
	v_max3_f32 v194, v194, v68, v69
	v_max3_f32 v194, v194, v70, v71
	v_max3_f32 v194, v194, v72, v73
	v_max3_f32 v194, v194, v74, v75
	v_max3_f32 v194, v194, v76, v77
	v_max3_f32 v194, v194, v78, v79
	v_mov_b32_e32 v195, v194
	s_nop 1
	v_permlane32_swap_b32_e32 v194, v195
	v_max_f32_e32 v195, v195, v195
	v_max_f32_e32 v194, v194, v194
	v_max_f32_e32 v194, v194, v195
	v_sub_f32_e32 v196, v194, v220
	v_cmp_ge_f32_e32 vcc, s30, v196
	s_cmp_eq_u64 vcc, exec
	s_waitcnt lgkmcnt(0)
	s_barrier
	s_cbranch_scc0 .Lslow_b1
	v_mov_b32_e32 v194, 1.0
